# stack: final rmsnorm + norm_x 4 rows in flight, S5 ktab table with per-n transcendentals computed once per wave (lane = n) and broadcast via LDS, 4-deep load pipeline
# speedup vs baseline: 1.0056x; 1.0056x over previous
; DI void sincos_rev(float rev, float& s, float& c) { const float f = rev - floorf(rev); s = __builtin_amdgcn_sinf(f); c = __builtin_amdgcn_cosf(f); }
; DI float2 cmul(float2 x, float2 y) { return make_float2(x.x * y.x - x.y * y.y, x.x * y.y + x.y * y.x); }
; DI S5c s5_load(const float* ldt, const float* lre, const float* lim, int layer, int d, int g, int n) {
;     const int ig = (layer * 2 + d) * S5G + g; const float dt = __expf(ldt[ig]);
;     S5c c; c.lr = lre[ig * 64 + n]; c.li = lim[ig * 64 + n]; c.a = c.lr * dt; c.b = c.li * dt; return c;
; }
; DI float2 cpowe(const S5c& c, float e) { const float mg = __expf(e * c.a); float s, co; sincos_rev(e * c.b * 0.15915494309189535f, s, co); return make_float2(mg * co, mg * s); }
; DI float2 s5_coef(const S5c& c) {
;     const float em1 = __expf(c.a) - 1.0f; float s, co, sh, ch; sincos_rev(c.b * 0.15915494309189535f, s, co); sincos_rev(c.b * 0.07957747154594768f, sh, ch); (void)ch;
;     const float sh2 = sh * sh, nr = em1 * co - (sh2 + sh2), ni = (em1 + 1.f) * s, den = c.lr * c.lr + c.li * c.li;
;     return make_float2((nr * c.lr + ni * c.li) / den, (ni * c.lr - nr * c.li) / den);
; }
; DI void phase_prep(const Params& P, int layer, int gtid, int nthr) {
;     ...
;     for (int idx = gtid; idx < S5G * 2 * 4 * 256; idx += nthr) {
;         const int q = idx & 15, p = (idx >> 4) & 15, kb = (idx >> 8) & 3, d = (idx >> 10) & 1, g = idx >> 11;
;         const int ig = (layer * 2 + d) * S5G + g; float acc[8];
; #pragma unroll
;         for (int k = 0; k < 8; ++k) acc[k] = 0.f;
;         for (int n = 0; n < 64; ++n) {
;             const S5c c = s5_load(ldt, lre, lim, layer, d, g, n);
;             const float2 bb = cmul(s5_coef(c), make_float2(bre[((size_t)ig * 64 + n) * 16 + q], bim[((size_t)ig * 64 + n) * 16 + q]));
;             const float2 cc = make_float2(cre[((size_t)ig * 16 + p) * 64 + n], cim[((size_t)ig * 16 + p) * 64 + n]);
;             float2 w = cmul(cmul(cc, bb), cpowe(c, (float)(8 * kb)));
;             const float2 l1 = cpowe(c, 1.0f);
; #pragma unroll
;             for (int k = 0; k < 8; ++k) { acc[k] += w.x; w = cmul(w, l1); }
.LBB0_322:
	v_bfe_u32 v29, v28, 10, 1
	v_or_b32_e32 v8, s16, v29
	v_ashrrev_i32_e32 v30, 11, v28
	v_mad_u32_u24 v12, v8, 24, v30
	v_ashrrev_i32_e32 v13, 31, v12
	v_lshl_add_u64 v[8:9], v[12:13], 2, s[24:25]
	global_load_dword v33, v[8:9], off
	v_lshlrev_b32_e32 v14, 6, v12
	v_lshlrev_b32_e32 v16, 2, v3
	v_lshlrev_b64 v[12:13], 12, v[12:13]
	v_ashrrev_i32_e32 v15, 31, v14
	s_movk_i32 s2, 0xf00
	v_and_or_b32 v22, v16, s2, v12
	v_mov_b32_e32 v23, v13
	v_lshl_add_u64 v[16:17], v[4:5], 0, v[12:13]
	v_lshl_add_u64 v[18:19], v[6:7], 0, v[12:13]
	v_lshlrev_b64 v[12:13], 2, v[14:15]
	v_lshl_add_u64 v[24:25], s[20:21], 0, v[12:13]
	v_lshl_add_u64 v[26:27], s[22:23], 0, v[12:13]
	v_lshrrev_b32_e32 v9, 5, v28
	v_mov_b32_e32 v8, 0
	v_and_b32_e32 v31, 24, v9
	s_mov_b64 s[8:9], 0
	v_mov_b32_e32 v9, v8
	v_mov_b32_e32 v10, v8
	v_mov_b32_e32 v11, v8
	v_cvt_f32_ubyte0_e32 v32, v31
	v_lshl_add_u64 v[20:21], s[42:43], 0, v[22:23]
	v_lshl_add_u64 v[22:23], s[46:47], 0, v[22:23]
	v_mov_b32_e32 v13, v8
	v_mov_b32_e32 v14, v8
	v_mov_b32_e32 v15, v8
	s_mov_b32 s2, 0x3da2f983
	s_waitcnt vmcnt(0)
	v_mul_f32_e32 v12, 0x3fb8aa3b, v33
	v_exp_f32_e32 v33, v12
	v_mov_b32_e32 v12, v8
	v_lshlrev_b32_e32 v66, 2, v233
	v_mov_b32_e32 v67, 0
	v_lshl_add_u64 v[68:69], v[26:27], 0, v[66:67]
	global_load_dword v37, v[68:69], off
	v_lshl_add_u64 v[68:69], v[24:25], 0, v[66:67]
	global_load_dword v36, v[68:69], off
	global_load_dword v72, v[16:17], off
	global_load_dword v73, v[18:19], off
	global_load_dword v74, v[20:21], off
	global_load_dword v75, v[22:23], off
	global_load_dword v76, v[16:17], off offset:64
	global_load_dword v77, v[18:19], off offset:64
	global_load_dword v78, v[20:21], off offset:4
	global_load_dword v79, v[22:23], off offset:4
	global_load_dword v80, v[16:17], off offset:128
	global_load_dword v81, v[18:19], off offset:128
	global_load_dword v82, v[20:21], off offset:8
	global_load_dword v83, v[22:23], off offset:8
	global_load_dword v84, v[16:17], off offset:192
	global_load_dword v85, v[18:19], off offset:192
	global_load_dword v86, v[20:21], off offset:12
	global_load_dword v87, v[22:23], off offset:12
	s_waitcnt vmcnt(16)
	v_mul_f32_e32 v39, v33, v37
	v_mul_f32_e32 v35, v33, v36
	v_pk_mul_f32 v[44:45], v[36:37], v[36:37]
	v_mov_b32_e32 v46, v37
	v_mul_f32_e32 v37, 0x3fb8aa3b, v35
	v_mul_f32_e32 v41, 0.15915494, v39
	v_mul_f32_e32 v43, 0x3da2f983, v39
	v_exp_f32_e32 v48, v37
	v_floor_f32_e32 v37, v41
	v_floor_f32_e32 v41, v43
	v_mul_f32_e32 v35, v35, v32
	v_mul_f32_e32 v47, v39, v32
	v_fma_f32 v37, v39, 0.15915494, -v37
	v_fma_f32 v39, v39, s2, -v41
	v_mul_f32_e32 v35, 0x3fb8aa3b, v35
	v_mul_f32_e32 v43, 0.15915494, v47
	v_sin_f32_e32 v53, v37
	v_cos_f32_e32 v54, v37
	v_sin_f32_e32 v37, v39
	v_exp_f32_e32 v50, v35
	v_floor_f32_e32 v35, v43
	v_fma_f32 v35, v47, 0.15915494, -v35
	v_sin_f32_e32 v57, v35
	v_cos_f32_e32 v56, v35
	v_add_f32_e32 v35, -1.0, v48
	v_mul_f32_e32 v37, v37, v37
	v_add_f32_e32 v59, 1.0, v35
	v_mul_f32_e32 v58, v35, v54
	v_mov_b32_e32 v55, v53
	v_add_f32_e32 v52, v37, v37
	v_pk_mul_f32 v[48:49], v[48:49], v[54:55] op_sel_hi:[0,1]
	v_pk_add_f32 v[54:55], v[58:59], v[52:53] neg_lo:[0,1] neg_hi:[0,1]
	v_pk_mul_f32 v[52:53], v[58:59], v[52:53]
	v_pk_mul_f32 v[50:51], v[50:51], v[56:57] op_sel_hi:[0,1]
	v_mov_b32_e32 v57, v53
	v_pk_mov_b32 v[52:53], v[52:53], v[54:55] op_sel:[1,0]
	v_mov_b32_e32 v56, v54
	v_pk_mul_f32 v[46:47], v[46:47], v[52:53] op_sel_hi:[0,1]
	v_pk_add_f32 v[44:45], v[44:45], v[44:45] op_sel:[0,1] op_sel_hi:[0,1]
	v_pk_fma_f32 v[52:53], v[36:37], v[54:55], v[46:47]
	v_pk_fma_f32 v[36:37], v[36:37], v[56:57], v[46:47] op_sel_hi:[0,1,1] neg_lo:[0,0,1] neg_hi:[0,0,1]
	v_div_scale_f32 v35, s[10:11], v45, v45, v37
	v_div_scale_f32 v39, s[10:11], v44, v44, v52
	v_rcp_f32_e32 v43, v35
	v_rcp_f32_e32 v46, v39
	v_div_scale_f32 v36, vcc, v37, v45, v37
	v_fma_f32 v47, -v35, v43, 1.0
	v_fma_f32 v53, -v39, v46, 1.0
	v_fmac_f32_e32 v43, v47, v43
	v_div_scale_f32 v41, s[10:11], v52, v44, v52
	v_fmac_f32_e32 v46, v53, v46
	v_mul_f32_e32 v47, v36, v43
	v_mul_f32_e32 v53, v41, v46
	v_fma_f32 v54, -v35, v47, v36
	v_fma_f32 v55, -v39, v53, v41
	v_fmac_f32_e32 v47, v54, v43
	v_fmac_f32_e32 v53, v55, v46
	v_fma_f32 v35, -v35, v47, v36
	v_fma_f32 v36, -v39, v53, v41
	v_div_fmas_f32 v35, v35, v43, v47
	s_mov_b64 vcc, s[10:11]
	v_div_fixup_f32 v37, v35, v45, v37
	v_div_fmas_f32 v35, v36, v46, v53
	v_div_fixup_f32 v36, v35, v44, v52
	v_lshrrev_b32_e32 v70, 6, v232
	v_mul_u32_u24_e32 v70, 0x600, v70
	v_mad_u32_u24 v66, v233, 24, v70
	ds_write_b64 v66, v[36:37]
	ds_write_b64 v66, v[48:49] offset:8
	ds_write_b64 v66, v[50:51] offset:16
	s_waitcnt lgkmcnt(0)
; DI float2 cpowe(const S5c& c, float e) { const float mg = __expf(e * c.a); float s, co; sincos_rev(e * c.b * 0.15915494309189535f, s, co); return make_float2(mg * co, mg * s); }
; DI float2 cmul(float2 x, float2 y) { return make_float2(x.x * y.x - x.y * y.y, x.x * y.y + x.y * y.x); }
; DI void phase_prep(const Params& P, int layer, int gtid, int nthr) {
;     ...
;         for (int n = 0; n < 64; ++n) {
;             const S5c c = s5_load(ldt, lre, lim, layer, d, g, n);
;             const float2 bb = cmul(s5_coef(c), make_float2(bre[((size_t)ig * 64 + n) * 16 + q], bim[((size_t)ig * 64 + n) * 16 + q]));
;             const float2 cc = make_float2(cre[((size_t)ig * 16 + p) * 64 + n], cim[((size_t)ig * 16 + p) * 64 + n]);
;             float2 w = cmul(cmul(cc, bb), cpowe(c, (float)(8 * kb)));
;             const float2 l1 = cpowe(c, 1.0f);
; #pragma unroll
;             for (int k = 0; k < 8; ++k) { acc[k] += w.x; w = cmul(w, l1); }
;         }
.LBB0_323:
	ds_read_b64 v[36:37], v70
	ds_read_b64 v[48:49], v70 offset:8
	ds_read_b64 v[50:51], v70 offset:16
	s_waitcnt vmcnt(12)
	v_mov_b32_e32 v38, v72
	v_mov_b32_e32 v40, v73
	v_mov_b32_e32 v42, v74
	v_mov_b32_e32 v34, v75
	s_add_u32 s8, s8, 4
	s_addc_u32 s9, s9, 0
	s_add_u32 s10, s8, 12
	s_and_b32 s10, s10, 0xfc
	s_mov_b32 s11, 0
	v_lshl_add_u64 v[66:67], v[20:21], 0, s[10:11]
	global_load_dword v74, v[66:67], off
	v_lshl_add_u64 v[66:67], v[22:23], 0, s[10:11]
	global_load_dword v75, v[66:67], off
	s_lshl_b32 s10, s10, 4
	v_lshl_add_u64 v[66:67], v[16:17], 0, s[10:11]
	global_load_dword v72, v[66:67], off
	v_lshl_add_u64 v[66:67], v[18:19], 0, s[10:11]
	global_load_dword v73, v[66:67], off
	s_waitcnt lgkmcnt(0)
	v_pk_mul_f32 v[40:41], v[40:41], v[36:37] op_sel:[0,1] op_sel_hi:[0,0]
	v_pk_fma_f32 v[44:45], v[38:39], v[36:37], v[40:41] op_sel_hi:[0,1,1] neg_lo:[0,0,1] neg_hi:[0,0,1]
	v_pk_fma_f32 v[36:37], v[38:39], v[36:37], v[40:41] op_sel_hi:[0,1,1]
	v_mov_b32_e32 v39, v37
	v_pk_mov_b32 v[36:37], v[36:37], v[44:45] op_sel:[1,0]
	v_mov_b32_e32 v38, v44
	v_pk_mul_f32 v[34:35], v[34:35], v[36:37] op_sel_hi:[0,1]
	v_pk_fma_f32 v[36:37], v[42:43], v[44:45], v[34:35] neg_lo:[0,0,1] neg_hi:[0,0,1]
	v_pk_fma_f32 v[34:35], v[42:43], v[38:39], v[34:35] op_sel_hi:[0,1,1]
	v_mov_b32_e32 v37, v35
	v_mul_f32_e32 v34, v51, v35
	v_pk_mul_f32 v[38:39], v[50:51], v[36:37] op_sel:[1,0] op_sel_hi:[0,1]
	v_pk_fma_f32 v[34:35], v[50:51], v[36:37], v[34:35] op_sel_hi:[1,1,0] neg_lo:[0,0,1] neg_hi:[0,0,1]
	v_pk_add_f32 v[36:37], v[38:39], v[38:39] op_sel:[0,1] op_sel_hi:[0,1]
	v_pk_mul_f32 v[36:37], v[48:49], v[36:37] op_sel:[1,0] op_sel_hi:[0,1]
	v_mov_b32_e32 v39, v34
	v_pk_fma_f32 v[40:41], v[48:49], v[34:35], v[36:37] op_sel_hi:[1,0,1] neg_lo:[0,0,1] neg_hi:[0,0,1]
	v_pk_fma_f32 v[34:35], v[48:49], v[34:35], v[36:37] op_sel_hi:[1,0,1]
	v_mov_b32_e32 v38, v40
	v_mov_b32_e32 v41, v35
	v_pk_mul_f32 v[36:37], v[48:49], v[40:41] op_sel:[1,0] op_sel_hi:[0,1]
	v_mul_f32_e32 v34, v49, v35
	v_pk_add_f32 v[36:37], v[36:37], v[36:37] op_sel:[0,1] op_sel_hi:[0,1]
	v_pk_fma_f32 v[34:35], v[48:49], v[40:41], v[34:35] op_sel_hi:[1,1,0] neg_lo:[0,0,1] neg_hi:[0,0,1]
	v_pk_mul_f32 v[36:37], v[48:49], v[36:37] op_sel:[1,0] op_sel_hi:[0,1]
	v_pk_add_f32 v[14:15], v[14:15], v[38:39]
	v_mov_b32_e32 v39, v34
	v_pk_fma_f32 v[40:41], v[48:49], v[34:35], v[36:37] op_sel_hi:[1,0,1] neg_lo:[0,0,1] neg_hi:[0,0,1]
	v_pk_fma_f32 v[34:35], v[48:49], v[34:35], v[36:37] op_sel_hi:[1,0,1]
	v_mov_b32_e32 v38, v40
	v_mov_b32_e32 v41, v35
	v_pk_mul_f32 v[36:37], v[48:49], v[40:41] op_sel:[1,0] op_sel_hi:[0,1]
	v_mul_f32_e32 v34, v49, v35
	v_pk_add_f32 v[36:37], v[36:37], v[36:37] op_sel:[0,1] op_sel_hi:[0,1]
	v_pk_fma_f32 v[34:35], v[48:49], v[40:41], v[34:35] op_sel_hi:[1,1,0] neg_lo:[0,0,1] neg_hi:[0,0,1]
	v_pk_mul_f32 v[36:37], v[48:49], v[36:37] op_sel:[1,0] op_sel_hi:[0,1]
	v_pk_add_f32 v[12:13], v[12:13], v[38:39]
	v_mov_b32_e32 v39, v34
	v_pk_fma_f32 v[40:41], v[48:49], v[34:35], v[36:37] op_sel_hi:[1,0,1] neg_lo:[0,0,1] neg_hi:[0,0,1]
	v_pk_fma_f32 v[34:35], v[48:49], v[34:35], v[36:37] op_sel_hi:[1,0,1]
	v_mov_b32_e32 v38, v40
	v_mov_b32_e32 v41, v35
	v_mul_f32_e32 v34, v49, v40
	v_mul_f32_e32 v36, v49, v35
	v_pk_fma_f32 v[34:35], v[48:49], v[40:41], v[34:35] op_sel:[1,0,0] op_sel_hi:[0,1,0]
	v_pk_fma_f32 v[36:37], v[48:49], v[40:41], v[36:37] op_sel_hi:[1,1,0] neg_lo:[0,0,1] neg_hi:[0,0,1]
	v_mul_f32_e32 v34, v49, v35
	v_mov_b32_e32 v37, v35
	v_pk_fma_f32 v[34:35], v[48:49], v[36:37], v[34:35] op_sel_hi:[1,1,0] neg_lo:[0,0,1] neg_hi:[0,0,1]
	v_pk_add_f32 v[10:11], v[10:11], v[38:39]
	v_mov_b32_e32 v35, v36
	v_pk_add_f32 v[8:9], v[8:9], v[34:35]
	ds_read_b64 v[36:37], v70 offset:24
	ds_read_b64 v[48:49], v70 offset:32
	ds_read_b64 v[50:51], v70 offset:40
	s_waitcnt vmcnt(12)
	v_mov_b32_e32 v38, v76
	v_mov_b32_e32 v40, v77
	v_mov_b32_e32 v42, v78
	v_mov_b32_e32 v34, v79
	s_add_u32 s8, s8, 4
	s_addc_u32 s9, s9, 0
	s_add_u32 s10, s8, 12
	s_and_b32 s10, s10, 0xfc
	s_mov_b32 s11, 0
	v_lshl_add_u64 v[66:67], v[20:21], 0, s[10:11]
	global_load_dword v78, v[66:67], off
	v_lshl_add_u64 v[66:67], v[22:23], 0, s[10:11]
	global_load_dword v79, v[66:67], off
	s_lshl_b32 s10, s10, 4
	v_lshl_add_u64 v[66:67], v[16:17], 0, s[10:11]
	global_load_dword v76, v[66:67], off
	v_lshl_add_u64 v[66:67], v[18:19], 0, s[10:11]
	global_load_dword v77, v[66:67], off
	s_waitcnt lgkmcnt(0)
; DI float2 cpowe(const S5c& c, float e) { const float mg = __expf(e * c.a); float s, co; sincos_rev(e * c.b * 0.15915494309189535f, s, co); return make_float2(mg * co, mg * s); }
; DI float2 cmul(float2 x, float2 y) { return make_float2(x.x * y.x - x.y * y.y, x.x * y.y + x.y * y.x); }
; DI void phase_prep(const Params& P, int layer, int gtid, int nthr) {
;     ...
;         for (int n = 0; n < 64; ++n) {
;             const S5c c = s5_load(ldt, lre, lim, layer, d, g, n);
;             const float2 bb = cmul(s5_coef(c), make_float2(bre[((size_t)ig * 64 + n) * 16 + q], bim[((size_t)ig * 64 + n) * 16 + q]));
;             const float2 cc = make_float2(cre[((size_t)ig * 16 + p) * 64 + n], cim[((size_t)ig * 16 + p) * 64 + n]);
;             float2 w = cmul(cmul(cc, bb), cpowe(c, (float)(8 * kb)));
;             const float2 l1 = cpowe(c, 1.0f);
; #pragma unroll
;             for (int k = 0; k < 8; ++k) { acc[k] += w.x; w = cmul(w, l1); }
;         }
	v_pk_mul_f32 v[40:41], v[40:41], v[36:37] op_sel:[0,1] op_sel_hi:[0,0]
	v_pk_fma_f32 v[44:45], v[38:39], v[36:37], v[40:41] op_sel_hi:[0,1,1] neg_lo:[0,0,1] neg_hi:[0,0,1]
	v_pk_fma_f32 v[36:37], v[38:39], v[36:37], v[40:41] op_sel_hi:[0,1,1]
	v_mov_b32_e32 v39, v37
	v_pk_mov_b32 v[36:37], v[36:37], v[44:45] op_sel:[1,0]
	v_mov_b32_e32 v38, v44
	v_pk_mul_f32 v[34:35], v[34:35], v[36:37] op_sel_hi:[0,1]
	v_pk_fma_f32 v[36:37], v[42:43], v[44:45], v[34:35] neg_lo:[0,0,1] neg_hi:[0,0,1]
	v_pk_fma_f32 v[34:35], v[42:43], v[38:39], v[34:35] op_sel_hi:[0,1,1]
	v_mov_b32_e32 v37, v35
	v_mul_f32_e32 v34, v51, v35
	v_pk_mul_f32 v[38:39], v[50:51], v[36:37] op_sel:[1,0] op_sel_hi:[0,1]
	v_pk_fma_f32 v[34:35], v[50:51], v[36:37], v[34:35] op_sel_hi:[1,1,0] neg_lo:[0,0,1] neg_hi:[0,0,1]
	v_pk_add_f32 v[36:37], v[38:39], v[38:39] op_sel:[0,1] op_sel_hi:[0,1]
	v_pk_mul_f32 v[36:37], v[48:49], v[36:37] op_sel:[1,0] op_sel_hi:[0,1]
	v_mov_b32_e32 v39, v34
	v_pk_fma_f32 v[40:41], v[48:49], v[34:35], v[36:37] op_sel_hi:[1,0,1] neg_lo:[0,0,1] neg_hi:[0,0,1]
	v_pk_fma_f32 v[34:35], v[48:49], v[34:35], v[36:37] op_sel_hi:[1,0,1]
	v_mov_b32_e32 v38, v40
	v_mov_b32_e32 v41, v35
	v_pk_mul_f32 v[36:37], v[48:49], v[40:41] op_sel:[1,0] op_sel_hi:[0,1]
	v_mul_f32_e32 v34, v49, v35
	v_pk_add_f32 v[36:37], v[36:37], v[36:37] op_sel:[0,1] op_sel_hi:[0,1]
	v_pk_fma_f32 v[34:35], v[48:49], v[40:41], v[34:35] op_sel_hi:[1,1,0] neg_lo:[0,0,1] neg_hi:[0,0,1]
	v_pk_mul_f32 v[36:37], v[48:49], v[36:37] op_sel:[1,0] op_sel_hi:[0,1]
	v_pk_add_f32 v[14:15], v[14:15], v[38:39]
	v_mov_b32_e32 v39, v34
	v_pk_fma_f32 v[40:41], v[48:49], v[34:35], v[36:37] op_sel_hi:[1,0,1] neg_lo:[0,0,1] neg_hi:[0,0,1]
	v_pk_fma_f32 v[34:35], v[48:49], v[34:35], v[36:37] op_sel_hi:[1,0,1]
	v_mov_b32_e32 v38, v40
	v_mov_b32_e32 v41, v35
	v_pk_mul_f32 v[36:37], v[48:49], v[40:41] op_sel:[1,0] op_sel_hi:[0,1]
	v_mul_f32_e32 v34, v49, v35
	v_pk_add_f32 v[36:37], v[36:37], v[36:37] op_sel:[0,1] op_sel_hi:[0,1]
	v_pk_fma_f32 v[34:35], v[48:49], v[40:41], v[34:35] op_sel_hi:[1,1,0] neg_lo:[0,0,1] neg_hi:[0,0,1]
	v_pk_mul_f32 v[36:37], v[48:49], v[36:37] op_sel:[1,0] op_sel_hi:[0,1]
	v_pk_add_f32 v[12:13], v[12:13], v[38:39]
	v_mov_b32_e32 v39, v34
	v_pk_fma_f32 v[40:41], v[48:49], v[34:35], v[36:37] op_sel_hi:[1,0,1] neg_lo:[0,0,1] neg_hi:[0,0,1]
	v_pk_fma_f32 v[34:35], v[48:49], v[34:35], v[36:37] op_sel_hi:[1,0,1]
	v_mov_b32_e32 v38, v40
	v_mov_b32_e32 v41, v35
	v_mul_f32_e32 v34, v49, v40
	v_mul_f32_e32 v36, v49, v35
	v_pk_fma_f32 v[34:35], v[48:49], v[40:41], v[34:35] op_sel:[1,0,0] op_sel_hi:[0,1,0]
	v_pk_fma_f32 v[36:37], v[48:49], v[40:41], v[36:37] op_sel_hi:[1,1,0] neg_lo:[0,0,1] neg_hi:[0,0,1]
	v_mul_f32_e32 v34, v49, v35
	v_mov_b32_e32 v37, v35
	v_pk_fma_f32 v[34:35], v[48:49], v[36:37], v[34:35] op_sel_hi:[1,1,0] neg_lo:[0,0,1] neg_hi:[0,0,1]
	v_pk_add_f32 v[10:11], v[10:11], v[38:39]
	v_mov_b32_e32 v35, v36
	v_pk_add_f32 v[8:9], v[8:9], v[34:35]
	ds_read_b64 v[36:37], v70 offset:48
	ds_read_b64 v[48:49], v70 offset:56
	ds_read_b64 v[50:51], v70 offset:64
	s_waitcnt vmcnt(12)
	v_mov_b32_e32 v38, v80
	v_mov_b32_e32 v40, v81
	v_mov_b32_e32 v42, v82
	v_mov_b32_e32 v34, v83
	s_add_u32 s8, s8, 4
	s_addc_u32 s9, s9, 0
	s_add_u32 s10, s8, 12
	s_and_b32 s10, s10, 0xfc
	s_mov_b32 s11, 0
	v_lshl_add_u64 v[66:67], v[20:21], 0, s[10:11]
	global_load_dword v82, v[66:67], off
	v_lshl_add_u64 v[66:67], v[22:23], 0, s[10:11]
	global_load_dword v83, v[66:67], off
	s_lshl_b32 s10, s10, 4
	v_lshl_add_u64 v[66:67], v[16:17], 0, s[10:11]
	global_load_dword v80, v[66:67], off
	v_lshl_add_u64 v[66:67], v[18:19], 0, s[10:11]
	global_load_dword v81, v[66:67], off
	s_waitcnt lgkmcnt(0)
	v_pk_mul_f32 v[40:41], v[40:41], v[36:37] op_sel:[0,1] op_sel_hi:[0,0]
	v_pk_fma_f32 v[44:45], v[38:39], v[36:37], v[40:41] op_sel_hi:[0,1,1] neg_lo:[0,0,1] neg_hi:[0,0,1]
	v_pk_fma_f32 v[36:37], v[38:39], v[36:37], v[40:41] op_sel_hi:[0,1,1]
	v_mov_b32_e32 v39, v37
	v_pk_mov_b32 v[36:37], v[36:37], v[44:45] op_sel:[1,0]
	v_mov_b32_e32 v38, v44
	v_pk_mul_f32 v[34:35], v[34:35], v[36:37] op_sel_hi:[0,1]
	v_pk_fma_f32 v[36:37], v[42:43], v[44:45], v[34:35] neg_lo:[0,0,1] neg_hi:[0,0,1]
	v_pk_fma_f32 v[34:35], v[42:43], v[38:39], v[34:35] op_sel_hi:[0,1,1]
	v_mov_b32_e32 v37, v35
	v_mul_f32_e32 v34, v51, v35
	v_pk_mul_f32 v[38:39], v[50:51], v[36:37] op_sel:[1,0] op_sel_hi:[0,1]
	v_pk_fma_f32 v[34:35], v[50:51], v[36:37], v[34:35] op_sel_hi:[1,1,0] neg_lo:[0,0,1] neg_hi:[0,0,1]
	v_pk_add_f32 v[36:37], v[38:39], v[38:39] op_sel:[0,1] op_sel_hi:[0,1]
	v_pk_mul_f32 v[36:37], v[48:49], v[36:37] op_sel:[1,0] op_sel_hi:[0,1]
	v_mov_b32_e32 v39, v34
	v_pk_fma_f32 v[40:41], v[48:49], v[34:35], v[36:37] op_sel_hi:[1,0,1] neg_lo:[0,0,1] neg_hi:[0,0,1]
	v_pk_fma_f32 v[34:35], v[48:49], v[34:35], v[36:37] op_sel_hi:[1,0,1]
	v_mov_b32_e32 v38, v40
	v_mov_b32_e32 v41, v35
	v_pk_mul_f32 v[36:37], v[48:49], v[40:41] op_sel:[1,0] op_sel_hi:[0,1]
	v_mul_f32_e32 v34, v49, v35
	v_pk_add_f32 v[36:37], v[36:37], v[36:37] op_sel:[0,1] op_sel_hi:[0,1]
	v_pk_fma_f32 v[34:35], v[48:49], v[40:41], v[34:35] op_sel_hi:[1,1,0] neg_lo:[0,0,1] neg_hi:[0,0,1]
	v_pk_mul_f32 v[36:37], v[48:49], v[36:37] op_sel:[1,0] op_sel_hi:[0,1]
	v_pk_add_f32 v[14:15], v[14:15], v[38:39]
	v_mov_b32_e32 v39, v34
	v_pk_fma_f32 v[40:41], v[48:49], v[34:35], v[36:37] op_sel_hi:[1,0,1] neg_lo:[0,0,1] neg_hi:[0,0,1]
	v_pk_fma_f32 v[34:35], v[48:49], v[34:35], v[36:37] op_sel_hi:[1,0,1]
	v_mov_b32_e32 v38, v40
	v_mov_b32_e32 v41, v35
	v_pk_mul_f32 v[36:37], v[48:49], v[40:41] op_sel:[1,0] op_sel_hi:[0,1]
	v_mul_f32_e32 v34, v49, v35
	v_pk_add_f32 v[36:37], v[36:37], v[36:37] op_sel:[0,1] op_sel_hi:[0,1]
	v_pk_fma_f32 v[34:35], v[48:49], v[40:41], v[34:35] op_sel_hi:[1,1,0] neg_lo:[0,0,1] neg_hi:[0,0,1]
	v_pk_mul_f32 v[36:37], v[48:49], v[36:37] op_sel:[1,0] op_sel_hi:[0,1]
	v_pk_add_f32 v[12:13], v[12:13], v[38:39]
	v_mov_b32_e32 v39, v34
	v_pk_fma_f32 v[40:41], v[48:49], v[34:35], v[36:37] op_sel_hi:[1,0,1] neg_lo:[0,0,1] neg_hi:[0,0,1]
	v_pk_fma_f32 v[34:35], v[48:49], v[34:35], v[36:37] op_sel_hi:[1,0,1]
	v_mov_b32_e32 v38, v40
	v_mov_b32_e32 v41, v35
	v_mul_f32_e32 v34, v49, v40
	v_mul_f32_e32 v36, v49, v35
	v_pk_fma_f32 v[34:35], v[48:49], v[40:41], v[34:35] op_sel:[1,0,0] op_sel_hi:[0,1,0]
	v_pk_fma_f32 v[36:37], v[48:49], v[40:41], v[36:37] op_sel_hi:[1,1,0] neg_lo:[0,0,1] neg_hi:[0,0,1]
	v_mul_f32_e32 v34, v49, v35
	v_mov_b32_e32 v37, v35
	v_pk_fma_f32 v[34:35], v[48:49], v[36:37], v[34:35] op_sel_hi:[1,1,0] neg_lo:[0,0,1] neg_hi:[0,0,1]
	v_pk_add_f32 v[10:11], v[10:11], v[38:39]
	v_mov_b32_e32 v35, v36
	v_pk_add_f32 v[8:9], v[8:9], v[34:35]
	ds_read_b64 v[36:37], v70 offset:72
	ds_read_b64 v[48:49], v70 offset:80
	ds_read_b64 v[50:51], v70 offset:88
	s_waitcnt vmcnt(12)
; DI float2 cpowe(const S5c& c, float e) { const float mg = __expf(e * c.a); float s, co; sincos_rev(e * c.b * 0.15915494309189535f, s, co); return make_float2(mg * co, mg * s); }
; DI float2 cmul(float2 x, float2 y) { return make_float2(x.x * y.x - x.y * y.y, x.x * y.y + x.y * y.x); }
; DI void phase_prep(const Params& P, int layer, int gtid, int nthr) {
;     ...
;         for (int n = 0; n < 64; ++n) {
;             const S5c c = s5_load(ldt, lre, lim, layer, d, g, n);
;             const float2 bb = cmul(s5_coef(c), make_float2(bre[((size_t)ig * 64 + n) * 16 + q], bim[((size_t)ig * 64 + n) * 16 + q]));
;             const float2 cc = make_float2(cre[((size_t)ig * 16 + p) * 64 + n], cim[((size_t)ig * 16 + p) * 64 + n]);
;             float2 w = cmul(cmul(cc, bb), cpowe(c, (float)(8 * kb)));
;             const float2 l1 = cpowe(c, 1.0f);
; #pragma unroll
;             for (int k = 0; k < 8; ++k) { acc[k] += w.x; w = cmul(w, l1); }
;         }
; #pragma unroll
;         for (int k = 0; k < 8; ++k) ktab[((((g * 2 + d) * 32 + 8 * kb + k) * 16 + p) * 16) + q] = acc[k];
;     }
	v_mov_b32_e32 v38, v84
	v_mov_b32_e32 v40, v85
	v_mov_b32_e32 v42, v86
	v_mov_b32_e32 v34, v87
	s_add_u32 s8, s8, 4
	s_addc_u32 s9, s9, 0
	s_add_u32 s10, s8, 12
	s_and_b32 s10, s10, 0xfc
	s_mov_b32 s11, 0
	v_lshl_add_u64 v[66:67], v[20:21], 0, s[10:11]
	global_load_dword v86, v[66:67], off
	v_lshl_add_u64 v[66:67], v[22:23], 0, s[10:11]
	global_load_dword v87, v[66:67], off
	s_lshl_b32 s10, s10, 4
	v_lshl_add_u64 v[66:67], v[16:17], 0, s[10:11]
	global_load_dword v84, v[66:67], off
	v_lshl_add_u64 v[66:67], v[18:19], 0, s[10:11]
	global_load_dword v85, v[66:67], off
	s_waitcnt lgkmcnt(0)
	v_pk_mul_f32 v[40:41], v[40:41], v[36:37] op_sel:[0,1] op_sel_hi:[0,0]
	v_pk_fma_f32 v[44:45], v[38:39], v[36:37], v[40:41] op_sel_hi:[0,1,1] neg_lo:[0,0,1] neg_hi:[0,0,1]
	v_pk_fma_f32 v[36:37], v[38:39], v[36:37], v[40:41] op_sel_hi:[0,1,1]
	v_mov_b32_e32 v39, v37
	v_pk_mov_b32 v[36:37], v[36:37], v[44:45] op_sel:[1,0]
	v_mov_b32_e32 v38, v44
	v_pk_mul_f32 v[34:35], v[34:35], v[36:37] op_sel_hi:[0,1]
	v_pk_fma_f32 v[36:37], v[42:43], v[44:45], v[34:35] neg_lo:[0,0,1] neg_hi:[0,0,1]
	v_pk_fma_f32 v[34:35], v[42:43], v[38:39], v[34:35] op_sel_hi:[0,1,1]
	v_mov_b32_e32 v37, v35
	v_mul_f32_e32 v34, v51, v35
	v_pk_mul_f32 v[38:39], v[50:51], v[36:37] op_sel:[1,0] op_sel_hi:[0,1]
	v_pk_fma_f32 v[34:35], v[50:51], v[36:37], v[34:35] op_sel_hi:[1,1,0] neg_lo:[0,0,1] neg_hi:[0,0,1]
	v_pk_add_f32 v[36:37], v[38:39], v[38:39] op_sel:[0,1] op_sel_hi:[0,1]
	v_pk_mul_f32 v[36:37], v[48:49], v[36:37] op_sel:[1,0] op_sel_hi:[0,1]
	v_mov_b32_e32 v39, v34
	v_pk_fma_f32 v[40:41], v[48:49], v[34:35], v[36:37] op_sel_hi:[1,0,1] neg_lo:[0,0,1] neg_hi:[0,0,1]
	v_pk_fma_f32 v[34:35], v[48:49], v[34:35], v[36:37] op_sel_hi:[1,0,1]
	v_mov_b32_e32 v38, v40
	v_mov_b32_e32 v41, v35
	v_pk_mul_f32 v[36:37], v[48:49], v[40:41] op_sel:[1,0] op_sel_hi:[0,1]
	v_mul_f32_e32 v34, v49, v35
	v_pk_add_f32 v[36:37], v[36:37], v[36:37] op_sel:[0,1] op_sel_hi:[0,1]
	v_pk_fma_f32 v[34:35], v[48:49], v[40:41], v[34:35] op_sel_hi:[1,1,0] neg_lo:[0,0,1] neg_hi:[0,0,1]
	v_pk_mul_f32 v[36:37], v[48:49], v[36:37] op_sel:[1,0] op_sel_hi:[0,1]
	v_pk_add_f32 v[14:15], v[14:15], v[38:39]
	v_mov_b32_e32 v39, v34
	v_pk_fma_f32 v[40:41], v[48:49], v[34:35], v[36:37] op_sel_hi:[1,0,1] neg_lo:[0,0,1] neg_hi:[0,0,1]
	v_pk_fma_f32 v[34:35], v[48:49], v[34:35], v[36:37] op_sel_hi:[1,0,1]
	v_mov_b32_e32 v38, v40
	v_mov_b32_e32 v41, v35
	v_pk_mul_f32 v[36:37], v[48:49], v[40:41] op_sel:[1,0] op_sel_hi:[0,1]
	v_mul_f32_e32 v34, v49, v35
	v_pk_add_f32 v[36:37], v[36:37], v[36:37] op_sel:[0,1] op_sel_hi:[0,1]
	v_pk_fma_f32 v[34:35], v[48:49], v[40:41], v[34:35] op_sel_hi:[1,1,0] neg_lo:[0,0,1] neg_hi:[0,0,1]
	v_pk_mul_f32 v[36:37], v[48:49], v[36:37] op_sel:[1,0] op_sel_hi:[0,1]
	v_pk_add_f32 v[12:13], v[12:13], v[38:39]
	v_mov_b32_e32 v39, v34
	v_pk_fma_f32 v[40:41], v[48:49], v[34:35], v[36:37] op_sel_hi:[1,0,1] neg_lo:[0,0,1] neg_hi:[0,0,1]
	v_pk_fma_f32 v[34:35], v[48:49], v[34:35], v[36:37] op_sel_hi:[1,0,1]
	v_mov_b32_e32 v38, v40
	v_mov_b32_e32 v41, v35
	v_mul_f32_e32 v34, v49, v40
	v_mul_f32_e32 v36, v49, v35
	v_pk_fma_f32 v[34:35], v[48:49], v[40:41], v[34:35] op_sel:[1,0,0] op_sel_hi:[0,1,0]
	v_pk_fma_f32 v[36:37], v[48:49], v[40:41], v[36:37] op_sel_hi:[1,1,0] neg_lo:[0,0,1] neg_hi:[0,0,1]
	v_mul_f32_e32 v34, v49, v35
	v_mov_b32_e32 v37, v35
	v_pk_fma_f32 v[34:35], v[48:49], v[36:37], v[34:35] op_sel_hi:[1,1,0] neg_lo:[0,0,1] neg_hi:[0,0,1]
	v_pk_add_f32 v[10:11], v[10:11], v[38:39]
	v_mov_b32_e32 v35, v36
	v_pk_add_f32 v[8:9], v[8:9], v[34:35]
	v_add_u32_e32 v70, 0x60, v70
	s_cmpk_eq_i32 s8, 0x100
	s_cbranch_scc0 .LBB0_323
	s_waitcnt vmcnt(0)
	v_lshlrev_b32_e32 v16, 6, v30
	v_lshlrev_b32_e32 v17, 5, v29
	v_or3_b32 v16, v17, v16, v31
	v_lshl_or_b32 v16, v16, 8, v1
	v_ashrrev_i32_e32 v17, 31, v16
	v_lshl_add_u64 v[16:17], v[16:17], 2, s[12:13]
	global_store_dword v[16:17], v15, off
	global_store_dword v[16:17], v14, off offset:1024
	global_store_dword v[16:17], v13, off offset:2048
	global_store_dword v[16:17], v12, off offset:3072
	v_add_co_u32_e32 v12, vcc, 0x1000, v16
	v_add_u32_e32 v28, s84, v28
	s_nop 0
	v_addc_co_u32_e32 v13, vcc, 0, v17, vcc
	s_mov_b32 s2, 0xbfff
	v_cmp_lt_i32_e32 vcc, s2, v28
	s_or_b64 s[14:15], vcc, s[14:15]
	v_add_u32_e32 v3, s0, v3
	global_store_dword v[12:13], v11, off
	global_store_dword v[12:13], v10, off offset:1024
	global_store_dword v[12:13], v9, off offset:2048
	global_store_dword v[12:13], v8, off offset:3072
	s_andn2_b64 exec, exec, s[14:15]
	s_cbranch_execnz .LBB0_322
